# lever 7 (instruction selection): P7 epilogue row sums through v_permlane16/32_swap instead of ds_bpermute LDS round trips; rest as v166
# baseline (speedup 1.0000x reference)
; __device__ __forceinline__ float fsigmoid(float v) { return __builtin_amdgcn_rcpf(1.0f + __builtin_amdgcn_exp2f(-1.4426950408889634f * v)); }
; __device__ __forceinline__ u32x4 ldnt(const bf16_t* p) { return __builtin_nontemporal_load((const u32x4*)p); }
;     __device__ __forceinline__ void fused(f32x4 (&acc)[2][2][4][2], const Unit& u, int wr, int wc, int fr, int fq, PG8_LAS unsigned char* lds, int wid, int lane) const {
;     ...
;                 for (int bj = 0; bj < 2; ++bj) { const size_t off = (size_t)(row0 + ai * HALF + m * 16) * 2048 + col0 + bj * HALF; hv[m][bj] = ldnt(hb + off); pl[m][bj] = ldnt(ple + off); }
; #pragma unroll
;             for (int m = 0; m < 4; ++m)
; #pragma unroll
;                 for (int bj = 0; bj < 2; ++bj)
; #pragma unroll
;                     for (int i = 0; i < 4; ++i) { acc[ai][bj][m][0][i] = fsigmoid(acc[ai][bj][m][0][i]); acc[ai][bj][m][1][i] = fsigmoid(acc[ai][bj][m][1][i]); }
.LBB0_584:
	s_lshl_b32 s6, s42, 8
	s_add_i32 s0, s6, s57
	v_or_b32_e32 v236, s0, v248
	v_lshrrev_b32_e32 v128, 1, v249
	v_ashrrev_i32_e32 v237, 31, v236
	v_and_or_b32 v224, v128, 24, s54
	v_lshlrev_b64 v[234:235], 11, v[236:237]
	v_or_b32_e32 v234, v234, v224
	v_lshlrev_b64 v[128:129], 1, v[234:235]
	v_lshl_add_u64 v[130:131], s[14:15], 0, v[128:129]
	s_barrier
	v_lshl_add_u64 v[128:129], s[2:3], 0, v[128:129]
	global_load_dwordx4 v[172:175], v[130:131], off nt
	global_load_dwordx4 v[164:167], v[130:131], off offset:256 nt
	global_load_dwordx4 v[168:171], v[128:129], off nt
	global_load_dwordx4 v[160:163], v[128:129], off offset:256 nt
	v_or_b32_e32 v128, 16, v236
	v_ashrrev_i32_e32 v129, 31, v128
	v_lshlrev_b64 v[232:233], 11, v[128:129]
	v_or_b32_e32 v232, v232, v224
	v_lshlrev_b64 v[128:129], 1, v[232:233]
	v_lshl_add_u64 v[130:131], s[14:15], 0, v[128:129]
	v_lshl_add_u64 v[128:129], s[2:3], 0, v[128:129]
	global_load_dwordx4 v[156:159], v[130:131], off nt
	global_load_dwordx4 v[148:151], v[130:131], off offset:256 nt
	global_load_dwordx4 v[152:155], v[128:129], off nt
	global_load_dwordx4 v[144:147], v[128:129], off offset:256 nt
	v_or_b32_e32 v128, 32, v236
	v_ashrrev_i32_e32 v129, 31, v128
	v_lshlrev_b64 v[230:231], 11, v[128:129]
	v_or_b32_e32 v230, v230, v224
	v_lshlrev_b64 v[128:129], 1, v[230:231]
	v_or_b32_e32 v176, 48, v236
	v_lshl_add_u64 v[130:131], s[14:15], 0, v[128:129]
	v_lshl_add_u64 v[128:129], s[2:3], 0, v[128:129]
	v_ashrrev_i32_e32 v177, 31, v176
	global_load_dwordx4 v[140:143], v[130:131], off nt
	global_load_dwordx4 v[132:135], v[130:131], off offset:256 nt
	global_load_dwordx4 v[136:139], v[128:129], off nt
	s_nop 0
	global_load_dwordx4 v[128:131], v[128:129], off offset:256 nt
	v_lshlrev_b64 v[228:229], 11, v[176:177]
	v_or_b32_e32 v228, v228, v224
	v_lshlrev_b64 v[176:177], 1, v[228:229]
	v_lshl_add_u64 v[192:193], s[14:15], 0, v[176:177]
	v_lshl_add_u64 v[194:195], s[2:3], 0, v[176:177]
	global_load_dwordx4 v[220:223], v[192:193], off nt
	global_load_dwordx4 v[200:203], v[192:193], off offset:256 nt
	global_load_dwordx4 v[216:219], v[194:195], off nt
	s_nop 0
	global_load_dwordx4 v[192:195], v[194:195], off offset:256 nt
	v_mul_f32_e32 v116, 0xbfb8aa3b, v116
	v_mul_f32_e32 v100, 0xbfb8aa3b, v100
	v_mul_f32_e32 v84, 0xbfb8aa3b, v84
	v_mul_f32_e32 v76, 0xbfb8aa3b, v76
	v_exp_f32_e32 v116, v116
	v_exp_f32_e32 v100, v100
	v_exp_f32_e32 v84, v84
	v_exp_f32_e32 v76, v76
	v_mul_f32_e32 v112, 0xbfb8aa3b, v112
	v_add_f32_e32 v116, 1.0, v116
	v_mul_f32_e32 v96, 0xbfb8aa3b, v96
	v_add_f32_e32 v100, 1.0, v100
	v_mul_f32_e32 v80, 0xbfb8aa3b, v80
	v_add_f32_e32 v84, 1.0, v84
	v_mul_f32_e32 v72, 0xbfb8aa3b, v72
	v_add_f32_e32 v76, 1.0, v76
	v_exp_f32_e32 v112, v112
	v_rcp_f32_e32 v204, v116
	v_mul_f32_e32 v116, 0xbfb8aa3b, v117
	v_exp_f32_e32 v96, v96
	v_rcp_f32_e32 v212, v100
	v_mul_f32_e32 v100, 0xbfb8aa3b, v101
	v_exp_f32_e32 v80, v80
	v_rcp_f32_e32 v180, v84
	v_mul_f32_e32 v84, 0xbfb8aa3b, v85
	v_exp_f32_e32 v72, v72
	v_rcp_f32_e32 v188, v76
	v_mul_f32_e32 v76, 0xbfb8aa3b, v77
	v_exp_f32_e32 v116, v116
	v_mul_f32_e32 v113, 0xbfb8aa3b, v113
	v_exp_f32_e32 v100, v100
	v_mul_f32_e32 v97, 0xbfb8aa3b, v97
	v_exp_f32_e32 v84, v84
	v_mul_f32_e32 v81, 0xbfb8aa3b, v81
	v_exp_f32_e32 v76, v76
	v_mul_f32_e32 v73, 0xbfb8aa3b, v73
	v_exp_f32_e32 v113, v113
	v_exp_f32_e32 v97, v97
	v_exp_f32_e32 v81, v81
	v_exp_f32_e32 v73, v73
	v_add_f32_e32 v112, 1.0, v112
	v_add_f32_e32 v96, 1.0, v96
	v_add_f32_e32 v80, 1.0, v80
	v_add_f32_e32 v72, 1.0, v72
	v_rcp_f32_e32 v196, v112
	v_add_f32_e32 v112, 1.0, v116
	v_rcp_f32_e32 v208, v96
	v_add_f32_e32 v96, 1.0, v100
	v_rcp_f32_e32 v176, v80
	v_add_f32_e32 v80, 1.0, v84
	v_rcp_f32_e32 v184, v72
	v_add_f32_e32 v72, 1.0, v76
	v_rcp_f32_e32 v205, v112
	v_add_f32_e32 v112, 1.0, v113
	v_mul_f32_e32 v113, 0xbfb8aa3b, v118
	v_rcp_f32_e32 v213, v96
	v_add_f32_e32 v96, 1.0, v97
	v_mul_f32_e32 v97, 0xbfb8aa3b, v102
	v_rcp_f32_e32 v181, v80
	v_add_f32_e32 v80, 1.0, v81
	v_mul_f32_e32 v81, 0xbfb8aa3b, v86
	v_rcp_f32_e32 v189, v72
	v_add_f32_e32 v72, 1.0, v73
	v_mul_f32_e32 v73, 0xbfb8aa3b, v78
	v_exp_f32_e32 v113, v113
	v_mul_f32_e32 v114, 0xbfb8aa3b, v114
	v_exp_f32_e32 v97, v97
	v_mul_f32_e32 v98, 0xbfb8aa3b, v98
	v_exp_f32_e32 v81, v81
	v_mul_f32_e32 v82, 0xbfb8aa3b, v82
	v_exp_f32_e32 v73, v73
	v_mul_f32_e32 v74, 0xbfb8aa3b, v74
	v_mul_f32_e32 v60, 0xbfb8aa3b, v60
	v_mul_f32_e32 v48, 0xbfb8aa3b, v48
	v_mul_f32_e32 v36, 0xbfb8aa3b, v36
	v_mul_f32_e32 v28, 0xbfb8aa3b, v28
	v_exp_f32_e32 v114, v114
	v_exp_f32_e32 v98, v98
	v_exp_f32_e32 v82, v82
	v_exp_f32_e32 v74, v74
	v_exp_f32_e32 v60, v60
	v_exp_f32_e32 v48, v48
	v_exp_f32_e32 v36, v36
	v_exp_f32_e32 v28, v28
	v_rcp_f32_e32 v197, v112
	v_add_f32_e32 v112, 1.0, v113
	v_mul_f32_e32 v113, 0xbfb8aa3b, v119
	v_rcp_f32_e32 v209, v96
	v_add_f32_e32 v96, 1.0, v97
	v_mul_f32_e32 v97, 0xbfb8aa3b, v103
	v_rcp_f32_e32 v177, v80
	v_add_f32_e32 v80, 1.0, v81
	v_mul_f32_e32 v81, 0xbfb8aa3b, v87
	v_rcp_f32_e32 v185, v72
	v_add_f32_e32 v72, 1.0, v73
	v_mul_f32_e32 v73, 0xbfb8aa3b, v79
	v_rcp_f32_e32 v206, v112
	v_add_f32_e32 v112, 1.0, v114
	v_exp_f32_e32 v113, v113
	v_mul_f32_e32 v114, 0xbfb8aa3b, v115
	v_rcp_f32_e32 v214, v96
	v_add_f32_e32 v96, 1.0, v98
	v_exp_f32_e32 v97, v97
	v_mul_f32_e32 v98, 0xbfb8aa3b, v99
	v_rcp_f32_e32 v182, v80
	v_add_f32_e32 v80, 1.0, v82
	v_exp_f32_e32 v81, v81
	v_mul_f32_e32 v82, 0xbfb8aa3b, v83
	v_rcp_f32_e32 v190, v72
	v_add_f32_e32 v72, 1.0, v74
	v_exp_f32_e32 v73, v73
	v_mul_f32_e32 v74, 0xbfb8aa3b, v75
	v_mul_f32_e32 v56, 0xbfb8aa3b, v56
	v_add_f32_e32 v60, 1.0, v60
	v_mul_f32_e32 v40, 0xbfb8aa3b, v40
	v_add_f32_e32 v48, 1.0, v48
; __device__ __forceinline__ float fsigmoid(float v) { return __builtin_amdgcn_rcpf(1.0f + __builtin_amdgcn_exp2f(-1.4426950408889634f * v)); }
; __device__ __forceinline__ float bf_lo(unsigned w) { return __uint_as_float(w << 16); }
; __device__ __forceinline__ float bf_hi(unsigned w) { return __uint_as_float(w & 0xffff0000u); }
;     __device__ __forceinline__ void fused(f32x4 (&acc)[2][2][4][2], const Unit& u, int wr, int wc, int fr, int fq, PG8_LAS unsigned char* lds, int wid, int lane) const {
;     ...
;                     for (int i = 0; i < 4; ++i) { acc[ai][bj][m][0][i] = fsigmoid(acc[ai][bj][m][0][i]); acc[ai][bj][m][1][i] = fsigmoid(acc[ai][bj][m][1][i]); }
;             asm volatile("" : "+v"(acc[ai][0][0][0]), "+v"(acc[ai][0][0][1]), "+v"(acc[ai][1][0][0]), "+v"(acc[ai][1][0][1]), "+v"(acc[ai][0][1][0]), "+v"(acc[ai][0][1][1]), "+v"(acc[ai][1][1][0]), "+v"(acc[ai][1][1][1]),
;                              "+v"(acc[ai][0][2][0]), "+v"(acc[ai][0][2][1]), "+v"(acc[ai][1][2][0]), "+v"(acc[ai][1][2][1]), "+v"(acc[ai][0][3][0]), "+v"(acc[ai][0][3][1]), "+v"(acc[ai][1][3][0]), "+v"(acc[ai][1][3][1]));
; #pragma unroll
;             for (int m = 0; m < 4; ++m) {
; #pragma unroll
;                 for (int bj = 0; bj < 2; ++bj) { const u32x4 h4 = hv[m][bj], p4 = pl[m][bj];
;                     const f32x4 h0 = (f32x4){bf_lo(h4.x), bf_hi(h4.x), bf_lo(h4.y), bf_hi(h4.y)}, h1 = (f32x4){bf_lo(h4.z), bf_hi(h4.z), bf_lo(h4.w), bf_hi(h4.w)};
;                     const f32x4 p0 = (f32x4){bf_lo(p4.x), bf_hi(p4.x), bf_lo(p4.y), bf_hi(p4.y)}, p1 = (f32x4){bf_lo(p4.z), bf_hi(p4.z), bf_lo(p4.w), bf_hi(p4.w)};
; #pragma unroll
;                     for (int i = 0; i < 4; ++i) { acc[ai][bj][m][0][i] = h0[i] + p0[i] * acc[ai][bj][m][0][i]; acc[ai][bj][m][1][i] = h1[i] + p1[i] * acc[ai][bj][m][1][i]; } }
	v_mul_f32_e32 v32, 0xbfb8aa3b, v32
	v_add_f32_e32 v36, 1.0, v36
	v_mul_f32_e32 v24, 0xbfb8aa3b, v24
	v_add_f32_e32 v28, 1.0, v28
	v_exp_f32_e32 v114, v114
	v_exp_f32_e32 v98, v98
	v_exp_f32_e32 v82, v82
	v_exp_f32_e32 v74, v74
	v_exp_f32_e32 v56, v56
	v_rcp_f32_e32 v76, v60
	v_mul_f32_e32 v60, 0xbfb8aa3b, v61
	v_exp_f32_e32 v40, v40
	v_rcp_f32_e32 v84, v48
	v_mul_f32_e32 v48, 0xbfb8aa3b, v49
	v_exp_f32_e32 v32, v32
	v_rcp_f32_e32 v100, v36
	v_mul_f32_e32 v36, 0xbfb8aa3b, v37
	v_exp_f32_e32 v24, v24
	v_rcp_f32_e32 v116, v28
	v_mul_f32_e32 v28, 0xbfb8aa3b, v29
	v_exp_f32_e32 v60, v60
	v_mul_f32_e32 v57, 0xbfb8aa3b, v57
	v_exp_f32_e32 v48, v48
	v_mul_f32_e32 v41, 0xbfb8aa3b, v41
	v_exp_f32_e32 v36, v36
	v_mul_f32_e32 v33, 0xbfb8aa3b, v33
	v_exp_f32_e32 v28, v28
	v_mul_f32_e32 v25, 0xbfb8aa3b, v25
	v_exp_f32_e32 v57, v57
	v_exp_f32_e32 v41, v41
	v_exp_f32_e32 v33, v33
	v_exp_f32_e32 v25, v25
	v_rcp_f32_e32 v198, v112
	v_add_f32_e32 v112, 1.0, v113
	v_rcp_f32_e32 v210, v96
	v_add_f32_e32 v96, 1.0, v97
	v_rcp_f32_e32 v178, v80
	v_add_f32_e32 v80, 1.0, v81
	v_rcp_f32_e32 v186, v72
	v_add_f32_e32 v72, 1.0, v73
	v_rcp_f32_e32 v207, v112
	v_add_f32_e32 v112, 1.0, v114
	v_rcp_f32_e32 v215, v96
	v_add_f32_e32 v96, 1.0, v98
	v_rcp_f32_e32 v183, v80
	v_add_f32_e32 v80, 1.0, v82
	v_rcp_f32_e32 v191, v72
	v_add_f32_e32 v72, 1.0, v74
	v_add_f32_e32 v56, 1.0, v56
	v_add_f32_e32 v40, 1.0, v40
	v_add_f32_e32 v32, 1.0, v32
	v_add_f32_e32 v24, 1.0, v24
	v_rcp_f32_e32 v199, v112
	v_rcp_f32_e32 v211, v96
	v_rcp_f32_e32 v179, v80
	v_rcp_f32_e32 v187, v72
	v_rcp_f32_e32 v72, v56
	v_add_f32_e32 v56, 1.0, v60
	v_rcp_f32_e32 v80, v40
	v_add_f32_e32 v40, 1.0, v48
	v_rcp_f32_e32 v96, v32
	v_add_f32_e32 v32, 1.0, v36
	v_rcp_f32_e32 v112, v24
	v_add_f32_e32 v24, 1.0, v28
	v_rcp_f32_e32 v77, v56
	v_add_f32_e32 v56, 1.0, v57
	v_mul_f32_e32 v57, 0xbfb8aa3b, v62
	v_rcp_f32_e32 v85, v40
	v_add_f32_e32 v40, 1.0, v41
	v_mul_f32_e32 v41, 0xbfb8aa3b, v50
	v_rcp_f32_e32 v101, v32
	v_add_f32_e32 v32, 1.0, v33
	v_mul_f32_e32 v33, 0xbfb8aa3b, v38
	v_rcp_f32_e32 v117, v24
	v_add_f32_e32 v24, 1.0, v25
	v_mul_f32_e32 v25, 0xbfb8aa3b, v30
	v_exp_f32_e32 v57, v57
	v_mul_f32_e32 v58, 0xbfb8aa3b, v58
	v_exp_f32_e32 v41, v41
	v_mul_f32_e32 v42, 0xbfb8aa3b, v42
	v_exp_f32_e32 v33, v33
	v_mul_f32_e32 v34, 0xbfb8aa3b, v34
	v_exp_f32_e32 v25, v25
	v_mul_f32_e32 v26, 0xbfb8aa3b, v26
	v_exp_f32_e32 v58, v58
	v_exp_f32_e32 v42, v42
	v_exp_f32_e32 v34, v34
	v_exp_f32_e32 v26, v26
	v_rcp_f32_e32 v73, v56
	v_add_f32_e32 v56, 1.0, v57
	v_mul_f32_e32 v57, 0xbfb8aa3b, v63
	v_rcp_f32_e32 v81, v40
	v_add_f32_e32 v40, 1.0, v41
	v_mul_f32_e32 v41, 0xbfb8aa3b, v51
	v_rcp_f32_e32 v97, v32
	v_add_f32_e32 v32, 1.0, v33
	v_mul_f32_e32 v33, 0xbfb8aa3b, v39
	v_rcp_f32_e32 v113, v24
	v_add_f32_e32 v24, 1.0, v25
	v_mul_f32_e32 v25, 0xbfb8aa3b, v31
	v_rcp_f32_e32 v78, v56
	v_add_f32_e32 v56, 1.0, v58
	v_exp_f32_e32 v57, v57
	v_mul_f32_e32 v58, 0xbfb8aa3b, v59
	v_rcp_f32_e32 v86, v40
	v_add_f32_e32 v40, 1.0, v42
	v_exp_f32_e32 v41, v41
	v_mul_f32_e32 v42, 0xbfb8aa3b, v43
	v_rcp_f32_e32 v102, v32
	v_add_f32_e32 v32, 1.0, v34
	v_exp_f32_e32 v33, v33
	v_mul_f32_e32 v34, 0xbfb8aa3b, v35
	v_rcp_f32_e32 v118, v24
	v_add_f32_e32 v24, 1.0, v26
	v_exp_f32_e32 v25, v25
	v_mul_f32_e32 v26, 0xbfb8aa3b, v27
	v_exp_f32_e32 v58, v58
	v_exp_f32_e32 v42, v42
	v_exp_f32_e32 v34, v34
	v_exp_f32_e32 v26, v26
	v_rcp_f32_e32 v74, v56
	v_add_f32_e32 v56, 1.0, v57
	v_rcp_f32_e32 v82, v40
	v_add_f32_e32 v40, 1.0, v41
	v_rcp_f32_e32 v98, v32
	v_add_f32_e32 v32, 1.0, v33
	v_rcp_f32_e32 v114, v24
	v_add_f32_e32 v24, 1.0, v25
	v_rcp_f32_e32 v79, v56
	v_add_f32_e32 v56, 1.0, v58
	v_rcp_f32_e32 v87, v40
	v_add_f32_e32 v40, 1.0, v42
	v_rcp_f32_e32 v103, v32
	v_add_f32_e32 v32, 1.0, v34
	v_rcp_f32_e32 v119, v24
	v_add_f32_e32 v24, 1.0, v26
	v_rcp_f32_e32 v75, v56
	v_rcp_f32_e32 v83, v40
	v_rcp_f32_e32 v99, v32
	v_rcp_f32_e32 v115, v24
	s_waitcnt vmcnt(0)
	v_lshlrev_b32_e32 v24, 16, v172
	v_and_b32_e32 v25, 0xffff0000, v172
	v_lshlrev_b32_e32 v26, 16, v168
	v_and_b32_e32 v27, 0xffff0000, v168
	v_lshlrev_b32_e32 v30, 16, v169
	v_pk_fma_f32 v[28:29], v[204:205], v[26:27], v[24:25]
	v_lshlrev_b32_e32 v24, 16, v174
	v_and_b32_e32 v25, 0xffff0000, v174
	v_lshlrev_b32_e32 v26, 16, v170
	v_and_b32_e32 v27, 0xffff0000, v170
	v_pk_fma_f32 v[24:25], v[196:197], v[26:27], v[24:25]
	v_lshlrev_b32_e32 v26, 16, v173
	v_and_b32_e32 v27, 0xffff0000, v173
	v_and_b32_e32 v31, 0xffff0000, v169
	v_pk_fma_f32 v[30:31], v[206:207], v[30:31], v[26:27]
	v_lshlrev_b32_e32 v26, 16, v175
	v_and_b32_e32 v27, 0xffff0000, v175
	v_lshlrev_b32_e32 v32, 16, v171
	v_and_b32_e32 v33, 0xffff0000, v171
	v_pk_fma_f32 v[26:27], v[198:199], v[32:33], v[26:27]
	v_lshlrev_b32_e32 v32, 16, v164
	v_and_b32_e32 v33, 0xffff0000, v164
	v_lshlrev_b32_e32 v34, 16, v160
	v_and_b32_e32 v35, 0xffff0000, v160
	v_pk_fma_f32 v[36:37], v[212:213], v[34:35], v[32:33]
	v_lshlrev_b32_e32 v32, 16, v166
	v_and_b32_e32 v33, 0xffff0000, v166
	v_lshlrev_b32_e32 v34, 16, v162
	v_and_b32_e32 v35, 0xffff0000, v162
	v_pk_fma_f32 v[32:33], v[208:209], v[34:35], v[32:33]
	v_lshlrev_b32_e32 v34, 16, v165
	v_and_b32_e32 v35, 0xffff0000, v165
	v_lshlrev_b32_e32 v38, 16, v161
	v_and_b32_e32 v39, 0xffff0000, v161
	v_pk_fma_f32 v[38:39], v[214:215], v[38:39], v[34:35]
	v_lshlrev_b32_e32 v34, 16, v167
	v_and_b32_e32 v35, 0xffff0000, v167
	v_lshlrev_b32_e32 v40, 16, v163
	v_and_b32_e32 v41, 0xffff0000, v163
	v_pk_fma_f32 v[34:35], v[210:211], v[40:41], v[34:35]
	v_lshlrev_b32_e32 v40, 16, v156
	v_and_b32_e32 v41, 0xffff0000, v156
	v_lshlrev_b32_e32 v42, 16, v152
	v_and_b32_e32 v43, 0xffff0000, v152
; __device__ __forceinline__ float fsigmoid(float v) { return __builtin_amdgcn_rcpf(1.0f + __builtin_amdgcn_exp2f(-1.4426950408889634f * v)); }
; __device__ __forceinline__ float bf_lo(unsigned w) { return __uint_as_float(w << 16); }
; __device__ __forceinline__ float bf_hi(unsigned w) { return __uint_as_float(w & 0xffff0000u); }
; __device__ __forceinline__ u32x4 ldnt(const bf16_t* p) { return __builtin_nontemporal_load((const u32x4*)p); }
;     __device__ __forceinline__ void fused(f32x4 (&acc)[2][2][4][2], const Unit& u, int wr, int wc, int fr, int fq, PG8_LAS unsigned char* lds, int wid, int lane) const {
;     ...
;                 for (int bj = 0; bj < 2; ++bj) { const size_t off = (size_t)(row0 + ai * HALF + m * 16) * 2048 + col0 + bj * HALF; hv[m][bj] = ldnt(hb + off); pl[m][bj] = ldnt(ple + off); }
; #pragma unroll
;             for (int m = 0; m < 4; ++m)
; #pragma unroll
;                 for (int bj = 0; bj < 2; ++bj)
; #pragma unroll
;                     for (int i = 0; i < 4; ++i) { acc[ai][bj][m][0][i] = fsigmoid(acc[ai][bj][m][0][i]); acc[ai][bj][m][1][i] = fsigmoid(acc[ai][bj][m][1][i]); }
;             asm volatile("" : "+v"(acc[ai][0][0][0]), "+v"(acc[ai][0][0][1]), "+v"(acc[ai][1][0][0]), "+v"(acc[ai][1][0][1]), "+v"(acc[ai][0][1][0]), "+v"(acc[ai][0][1][1]), "+v"(acc[ai][1][1][0]), "+v"(acc[ai][1][1][1]),
;                              "+v"(acc[ai][0][2][0]), "+v"(acc[ai][0][2][1]), "+v"(acc[ai][1][2][0]), "+v"(acc[ai][1][2][1]), "+v"(acc[ai][0][3][0]), "+v"(acc[ai][0][3][1]), "+v"(acc[ai][1][3][0]), "+v"(acc[ai][1][3][1]));
; #pragma unroll
;             for (int m = 0; m < 4; ++m) {
; #pragma unroll
;                 for (int bj = 0; bj < 2; ++bj) { const u32x4 h4 = hv[m][bj], p4 = pl[m][bj];
;                     const f32x4 h0 = (f32x4){bf_lo(h4.x), bf_hi(h4.x), bf_lo(h4.y), bf_hi(h4.y)}, h1 = (f32x4){bf_lo(h4.z), bf_hi(h4.z), bf_lo(h4.w), bf_hi(h4.w)};
;                     const f32x4 p0 = (f32x4){bf_lo(p4.x), bf_hi(p4.x), bf_lo(p4.y), bf_hi(p4.y)}, p1 = (f32x4){bf_lo(p4.z), bf_hi(p4.z), bf_lo(p4.w), bf_hi(p4.w)};
; #pragma unroll
;                     for (int i = 0; i < 4; ++i) { acc[ai][bj][m][0][i] = h0[i] + p0[i] * acc[ai][bj][m][0][i]; acc[ai][bj][m][1][i] = h1[i] + p1[i] * acc[ai][bj][m][1][i]; } }
	v_pk_fma_f32 v[48:49], v[180:181], v[42:43], v[40:41]
	v_lshlrev_b32_e32 v40, 16, v158
	v_and_b32_e32 v41, 0xffff0000, v158
	v_lshlrev_b32_e32 v42, 16, v154
	v_and_b32_e32 v43, 0xffff0000, v154
	v_pk_fma_f32 v[40:41], v[176:177], v[42:43], v[40:41]
	v_lshlrev_b32_e32 v42, 16, v157
	v_and_b32_e32 v43, 0xffff0000, v157
	v_lshlrev_b32_e32 v50, 16, v153
	v_and_b32_e32 v51, 0xffff0000, v153
	v_pk_fma_f32 v[50:51], v[182:183], v[50:51], v[42:43]
	v_lshlrev_b32_e32 v42, 16, v159
	v_and_b32_e32 v43, 0xffff0000, v159
	v_lshlrev_b32_e32 v56, 16, v155
	v_and_b32_e32 v57, 0xffff0000, v155
	v_pk_fma_f32 v[42:43], v[178:179], v[56:57], v[42:43]
	v_lshlrev_b32_e32 v56, 16, v148
	v_and_b32_e32 v57, 0xffff0000, v148
	v_lshlrev_b32_e32 v58, 16, v144
	v_and_b32_e32 v59, 0xffff0000, v144
	v_pk_fma_f32 v[60:61], v[188:189], v[58:59], v[56:57]
	v_lshlrev_b32_e32 v56, 16, v150
	v_and_b32_e32 v57, 0xffff0000, v150
	v_lshlrev_b32_e32 v58, 16, v146
	v_and_b32_e32 v59, 0xffff0000, v146
	v_pk_fma_f32 v[56:57], v[184:185], v[58:59], v[56:57]
	v_lshlrev_b32_e32 v58, 16, v149
	v_and_b32_e32 v59, 0xffff0000, v149
	v_lshlrev_b32_e32 v62, 16, v145
	v_and_b32_e32 v63, 0xffff0000, v145
	v_pk_fma_f32 v[62:63], v[190:191], v[62:63], v[58:59]
	v_lshlrev_b32_e32 v58, 16, v151
	v_and_b32_e32 v59, 0xffff0000, v151
	v_lshlrev_b32_e32 v144, 16, v147
	v_and_b32_e32 v145, 0xffff0000, v147
	v_pk_fma_f32 v[58:59], v[186:187], v[144:145], v[58:59]
	v_lshlrev_b32_e32 v144, 16, v140
	v_and_b32_e32 v145, 0xffff0000, v140
	v_lshlrev_b32_e32 v146, 16, v136
	v_and_b32_e32 v147, 0xffff0000, v136
	v_lshlrev_b32_e32 v140, 16, v141
	v_and_b32_e32 v141, 0xffff0000, v141
	v_lshlrev_b32_e32 v136, 16, v137
	v_and_b32_e32 v137, 0xffff0000, v137
	v_pk_fma_f32 v[76:77], v[76:77], v[146:147], v[144:145]
	v_lshlrev_b32_e32 v146, 16, v138
	v_and_b32_e32 v147, 0xffff0000, v138
	v_pk_fma_f32 v[78:79], v[78:79], v[136:137], v[140:141]
	v_lshlrev_b32_e32 v136, 16, v143
	v_and_b32_e32 v137, 0xffff0000, v143
	v_lshlrev_b32_e32 v138, 16, v139
	v_and_b32_e32 v139, 0xffff0000, v139
	v_pk_fma_f32 v[74:75], v[74:75], v[138:139], v[136:137]
	v_lshlrev_b32_e32 v136, 16, v132
	v_and_b32_e32 v137, 0xffff0000, v132
	v_lshlrev_b32_e32 v138, 16, v128
	v_and_b32_e32 v139, 0xffff0000, v128
	v_lshlrev_b32_e32 v132, 16, v133
	v_and_b32_e32 v133, 0xffff0000, v133
	v_lshlrev_b32_e32 v128, 16, v129
	v_and_b32_e32 v129, 0xffff0000, v129
	v_pk_fma_f32 v[84:85], v[84:85], v[138:139], v[136:137]
	v_lshlrev_b32_e32 v138, 16, v130
	v_and_b32_e32 v139, 0xffff0000, v130
	v_pk_fma_f32 v[86:87], v[86:87], v[128:129], v[132:133]
	v_lshlrev_b32_e32 v128, 16, v135
	v_and_b32_e32 v129, 0xffff0000, v135
	v_lshlrev_b32_e32 v130, 16, v131
	v_and_b32_e32 v131, 0xffff0000, v131
	v_pk_fma_f32 v[82:83], v[82:83], v[130:131], v[128:129]
	v_lshlrev_b32_e32 v128, 16, v220
	v_and_b32_e32 v129, 0xffff0000, v220
	v_lshlrev_b32_e32 v130, 16, v216
	v_and_b32_e32 v131, 0xffff0000, v216
	v_pk_fma_f32 v[100:101], v[100:101], v[130:131], v[128:129]
	v_lshlrev_b32_e32 v128, 16, v222
	v_and_b32_e32 v129, 0xffff0000, v222
	v_lshlrev_b32_e32 v130, 16, v218
	v_and_b32_e32 v131, 0xffff0000, v218
	v_pk_fma_f32 v[96:97], v[96:97], v[130:131], v[128:129]
	v_lshlrev_b32_e32 v128, 16, v221
	v_and_b32_e32 v129, 0xffff0000, v221
	v_lshlrev_b32_e32 v130, 16, v217
	v_and_b32_e32 v131, 0xffff0000, v217
	v_pk_fma_f32 v[102:103], v[102:103], v[130:131], v[128:129]
	v_lshlrev_b32_e32 v128, 16, v223
	v_and_b32_e32 v129, 0xffff0000, v223
	v_lshlrev_b32_e32 v130, 16, v219
	v_and_b32_e32 v131, 0xffff0000, v219
	v_pk_fma_f32 v[98:99], v[98:99], v[130:131], v[128:129]
	v_lshlrev_b32_e32 v128, 16, v200
	v_and_b32_e32 v129, 0xffff0000, v200
	v_lshlrev_b32_e32 v130, 16, v192
	v_and_b32_e32 v131, 0xffff0000, v192
	v_pk_fma_f32 v[116:117], v[116:117], v[130:131], v[128:129]
	v_lshlrev_b32_e32 v128, 16, v202
	v_and_b32_e32 v129, 0xffff0000, v202
	v_lshlrev_b32_e32 v130, 16, v194
	v_and_b32_e32 v131, 0xffff0000, v194
	v_pk_fma_f32 v[112:113], v[112:113], v[130:131], v[128:129]
	v_lshlrev_b32_e32 v128, 16, v201
	v_and_b32_e32 v129, 0xffff0000, v201
	v_lshlrev_b32_e32 v130, 16, v193
	v_and_b32_e32 v131, 0xffff0000, v193
	v_pk_fma_f32 v[118:119], v[118:119], v[130:131], v[128:129]
	v_lshlrev_b32_e32 v128, 16, v203
	v_and_b32_e32 v129, 0xffff0000, v203
	v_lshlrev_b32_e32 v130, 16, v195
	v_and_b32_e32 v131, 0xffff0000, v195
	v_pk_fma_f32 v[114:115], v[114:115], v[130:131], v[128:129]
	v_add_u32_e32 v128, 0x80, v236
	v_ashrrev_i32_e32 v129, 31, v128
	v_lshlrev_b64 v[242:243], 11, v[128:129]
	v_or_b32_e32 v242, v242, v224
	v_lshlrev_b32_e32 v144, 16, v142
	v_and_b32_e32 v145, 0xffff0000, v142
	v_lshlrev_b32_e32 v136, 16, v134
	v_and_b32_e32 v137, 0xffff0000, v134
	v_lshlrev_b64 v[128:129], 1, v[242:243]
	v_pk_fma_f32 v[72:73], v[72:73], v[146:147], v[144:145]
	v_pk_fma_f32 v[80:81], v[80:81], v[138:139], v[136:137]
	v_lshl_add_u64 v[130:131], s[14:15], 0, v[128:129]
	v_lshl_add_u64 v[128:129], s[2:3], 0, v[128:129]
	global_load_dwordx4 v[172:175], v[130:131], off nt
	global_load_dwordx4 v[164:167], v[130:131], off offset:256 nt
	global_load_dwordx4 v[168:171], v[128:129], off nt
	global_load_dwordx4 v[160:163], v[128:129], off offset:256 nt
	v_add_u32_e32 v128, 0x90, v236
	v_ashrrev_i32_e32 v129, 31, v128
	v_lshlrev_b64 v[240:241], 11, v[128:129]
	v_or_b32_e32 v240, v240, v224
	v_lshlrev_b64 v[128:129], 1, v[240:241]
	v_lshl_add_u64 v[130:131], s[14:15], 0, v[128:129]
	v_lshl_add_u64 v[128:129], s[2:3], 0, v[128:129]
	global_load_dwordx4 v[156:159], v[130:131], off nt
	global_load_dwordx4 v[148:151], v[130:131], off offset:256 nt
	global_load_dwordx4 v[152:155], v[128:129], off nt
; __device__ __forceinline__ float fsigmoid(float v) { return __builtin_amdgcn_rcpf(1.0f + __builtin_amdgcn_exp2f(-1.4426950408889634f * v)); }
; __device__ __forceinline__ u32x4 ldnt(const bf16_t* p) { return __builtin_nontemporal_load((const u32x4*)p); }
;     __device__ __forceinline__ void fused(f32x4 (&acc)[2][2][4][2], const Unit& u, int wr, int wc, int fr, int fq, PG8_LAS unsigned char* lds, int wid, int lane) const {
;     ...
;                 for (int bj = 0; bj < 2; ++bj) { const size_t off = (size_t)(row0 + ai * HALF + m * 16) * 2048 + col0 + bj * HALF; hv[m][bj] = ldnt(hb + off); pl[m][bj] = ldnt(ple + off); }
; #pragma unroll
;             for (int m = 0; m < 4; ++m)
; #pragma unroll
;                 for (int bj = 0; bj < 2; ++bj)
; #pragma unroll
;                     for (int i = 0; i < 4; ++i) { acc[ai][bj][m][0][i] = fsigmoid(acc[ai][bj][m][0][i]); acc[ai][bj][m][1][i] = fsigmoid(acc[ai][bj][m][1][i]); }
	global_load_dwordx4 v[144:147], v[128:129], off offset:256 nt
	v_add_u32_e32 v128, 0xa0, v236
	v_ashrrev_i32_e32 v129, 31, v128
	v_lshlrev_b64 v[238:239], 11, v[128:129]
	v_or_b32_e32 v238, v238, v224
	v_lshlrev_b64 v[128:129], 1, v[238:239]
	v_add_u32_e32 v176, 0xb0, v236
	v_lshl_add_u64 v[130:131], s[14:15], 0, v[128:129]
	v_lshl_add_u64 v[128:129], s[2:3], 0, v[128:129]
	v_ashrrev_i32_e32 v177, 31, v176
	global_load_dwordx4 v[140:143], v[130:131], off nt
	global_load_dwordx4 v[132:135], v[130:131], off offset:256 nt
	global_load_dwordx4 v[136:139], v[128:129], off nt
	s_nop 0
	global_load_dwordx4 v[128:131], v[128:129], off offset:256 nt
	v_lshlrev_b64 v[236:237], 11, v[176:177]
	v_or_b32_e32 v236, v236, v224
	v_lshlrev_b64 v[176:177], 1, v[236:237]
	v_lshl_add_u64 v[192:193], s[14:15], 0, v[176:177]
	v_lshl_add_u64 v[194:195], s[2:3], 0, v[176:177]
	global_load_dwordx4 v[220:223], v[192:193], off nt
	global_load_dwordx4 v[200:203], v[192:193], off offset:256 nt
	global_load_dwordx4 v[216:219], v[194:195], off nt
	s_nop 0
	global_load_dwordx4 v[192:195], v[194:195], off offset:256 nt
	v_mul_f32_e32 v124, 0xbfb8aa3b, v124
	v_mul_f32_e32 v108, 0xbfb8aa3b, v108
	v_mul_f32_e32 v92, 0xbfb8aa3b, v92
	v_mul_f32_e32 v68, 0xbfb8aa3b, v68
	v_exp_f32_e32 v124, v124
	v_exp_f32_e32 v108, v108
	v_exp_f32_e32 v92, v92
	v_exp_f32_e32 v68, v68
	v_mul_f32_e32 v120, 0xbfb8aa3b, v120
	v_add_f32_e32 v124, 1.0, v124
	v_mul_f32_e32 v104, 0xbfb8aa3b, v104
	v_add_f32_e32 v108, 1.0, v108
	v_mul_f32_e32 v88, 0xbfb8aa3b, v88
	v_add_f32_e32 v92, 1.0, v92
	v_mul_f32_e32 v64, 0xbfb8aa3b, v64
	v_add_f32_e32 v68, 1.0, v68
	v_exp_f32_e32 v120, v120
	v_rcp_f32_e32 v204, v124
	v_mul_f32_e32 v124, 0xbfb8aa3b, v125
	v_exp_f32_e32 v104, v104
	v_rcp_f32_e32 v212, v108
	v_mul_f32_e32 v108, 0xbfb8aa3b, v109
	v_exp_f32_e32 v88, v88
	v_rcp_f32_e32 v180, v92
	v_mul_f32_e32 v92, 0xbfb8aa3b, v93
	v_exp_f32_e32 v64, v64
	v_rcp_f32_e32 v188, v68
	v_mul_f32_e32 v68, 0xbfb8aa3b, v69
	v_exp_f32_e32 v124, v124
	v_mul_f32_e32 v121, 0xbfb8aa3b, v121
	v_exp_f32_e32 v108, v108
	v_mul_f32_e32 v105, 0xbfb8aa3b, v105
	v_exp_f32_e32 v92, v92
	v_mul_f32_e32 v89, 0xbfb8aa3b, v89
	v_exp_f32_e32 v68, v68
	v_mul_f32_e32 v65, 0xbfb8aa3b, v65
	v_exp_f32_e32 v121, v121
	v_exp_f32_e32 v105, v105
	v_exp_f32_e32 v89, v89
	v_exp_f32_e32 v65, v65
	v_add_f32_e32 v120, 1.0, v120
	v_add_f32_e32 v104, 1.0, v104
	v_add_f32_e32 v88, 1.0, v88
	v_add_f32_e32 v64, 1.0, v64
	v_rcp_f32_e32 v196, v120
	v_add_f32_e32 v120, 1.0, v124
	v_rcp_f32_e32 v208, v104
	v_add_f32_e32 v104, 1.0, v108
	v_rcp_f32_e32 v176, v88
	v_add_f32_e32 v88, 1.0, v92
	v_rcp_f32_e32 v184, v64
	v_add_f32_e32 v64, 1.0, v68
	v_rcp_f32_e32 v205, v120
	v_add_f32_e32 v120, 1.0, v121
	v_mul_f32_e32 v121, 0xbfb8aa3b, v126
	v_rcp_f32_e32 v213, v104
	v_add_f32_e32 v104, 1.0, v105
	v_mul_f32_e32 v105, 0xbfb8aa3b, v110
	v_rcp_f32_e32 v181, v88
	v_add_f32_e32 v88, 1.0, v89
	v_mul_f32_e32 v89, 0xbfb8aa3b, v94
	v_rcp_f32_e32 v189, v64
	v_add_f32_e32 v64, 1.0, v65
	v_mul_f32_e32 v65, 0xbfb8aa3b, v70
	v_exp_f32_e32 v121, v121
	v_mul_f32_e32 v122, 0xbfb8aa3b, v122
	v_exp_f32_e32 v105, v105
	v_mul_f32_e32 v106, 0xbfb8aa3b, v106
	v_exp_f32_e32 v89, v89
	v_mul_f32_e32 v90, 0xbfb8aa3b, v90
	v_exp_f32_e32 v65, v65
	v_mul_f32_e32 v66, 0xbfb8aa3b, v66
	v_mul_f32_e32 v52, 0xbfb8aa3b, v52
	v_mul_f32_e32 v20, 0xbfb8aa3b, v20
	v_mul_f32_e32 v12, 0xbfb8aa3b, v12
	v_mul_f32_e32 v4, 0xbfb8aa3b, v4
	v_exp_f32_e32 v122, v122
	v_exp_f32_e32 v106, v106
	v_exp_f32_e32 v90, v90
	v_exp_f32_e32 v66, v66
	v_exp_f32_e32 v52, v52
	v_exp_f32_e32 v20, v20
	v_exp_f32_e32 v12, v12
	v_exp_f32_e32 v4, v4
	v_rcp_f32_e32 v197, v120
	v_add_f32_e32 v120, 1.0, v121
	v_mul_f32_e32 v121, 0xbfb8aa3b, v127
	v_rcp_f32_e32 v209, v104
	v_add_f32_e32 v104, 1.0, v105
	v_mul_f32_e32 v105, 0xbfb8aa3b, v111
	v_rcp_f32_e32 v177, v88
	v_add_f32_e32 v88, 1.0, v89
	v_mul_f32_e32 v89, 0xbfb8aa3b, v95
	v_rcp_f32_e32 v185, v64
	v_add_f32_e32 v64, 1.0, v65
	v_mul_f32_e32 v65, 0xbfb8aa3b, v71
	v_rcp_f32_e32 v206, v120
	v_add_f32_e32 v120, 1.0, v122
	v_exp_f32_e32 v121, v121
	v_mul_f32_e32 v122, 0xbfb8aa3b, v123
	v_rcp_f32_e32 v214, v104
	v_add_f32_e32 v104, 1.0, v106
	v_exp_f32_e32 v105, v105
	v_mul_f32_e32 v106, 0xbfb8aa3b, v107
	v_rcp_f32_e32 v182, v88
	v_add_f32_e32 v88, 1.0, v90
	v_exp_f32_e32 v89, v89
	v_mul_f32_e32 v90, 0xbfb8aa3b, v91
	v_rcp_f32_e32 v190, v64
	v_add_f32_e32 v64, 1.0, v66
	v_exp_f32_e32 v65, v65
	v_mul_f32_e32 v66, 0xbfb8aa3b, v67
	v_mul_f32_e32 v44, 0xbfb8aa3b, v44
	v_add_f32_e32 v52, 1.0, v52
	v_mul_f32_e32 v16, 0xbfb8aa3b, v16
	v_add_f32_e32 v20, 1.0, v20
	v_mul_f32_e32 v8, 0xbfb8aa3b, v8
	v_add_f32_e32 v12, 1.0, v12
	v_mul_f32_e32 v0, 0xbfb8aa3b, v0
	v_add_f32_e32 v4, 1.0, v4
	v_exp_f32_e32 v122, v122
	v_exp_f32_e32 v106, v106
	v_exp_f32_e32 v90, v90
	v_exp_f32_e32 v66, v66
	v_exp_f32_e32 v44, v44
	v_rcp_f32_e32 v68, v52
	v_mul_f32_e32 v52, 0xbfb8aa3b, v53
	v_exp_f32_e32 v16, v16
	v_rcp_f32_e32 v92, v20
	v_mul_f32_e32 v20, 0xbfb8aa3b, v21
	v_exp_f32_e32 v8, v8
	v_rcp_f32_e32 v108, v12
	v_mul_f32_e32 v12, 0xbfb8aa3b, v13
	v_exp_f32_e32 v0, v0
	v_rcp_f32_e32 v124, v4
	v_mul_f32_e32 v4, 0xbfb8aa3b, v5
	v_exp_f32_e32 v52, v52
	v_mul_f32_e32 v45, 0xbfb8aa3b, v45
	v_exp_f32_e32 v20, v20
	v_mul_f32_e32 v17, 0xbfb8aa3b, v17
	v_exp_f32_e32 v12, v12
	v_mul_f32_e32 v9, 0xbfb8aa3b, v9
	v_exp_f32_e32 v4, v4
	v_mul_f32_e32 v1, 0xbfb8aa3b, v1
	v_exp_f32_e32 v45, v45
	v_exp_f32_e32 v17, v17
	v_exp_f32_e32 v9, v9
	v_exp_f32_e32 v1, v1
	v_rcp_f32_e32 v198, v120
	v_add_f32_e32 v120, 1.0, v121
	v_rcp_f32_e32 v210, v104
	v_add_f32_e32 v104, 1.0, v105
	v_rcp_f32_e32 v178, v88
	v_add_f32_e32 v88, 1.0, v89
; __device__ __forceinline__ float fsigmoid(float v) { return __builtin_amdgcn_rcpf(1.0f + __builtin_amdgcn_exp2f(-1.4426950408889634f * v)); }
; __device__ __forceinline__ float bf_lo(unsigned w) { return __uint_as_float(w << 16); }
; __device__ __forceinline__ float bf_hi(unsigned w) { return __uint_as_float(w & 0xffff0000u); }
;     __device__ __forceinline__ void fused(f32x4 (&acc)[2][2][4][2], const Unit& u, int wr, int wc, int fr, int fq, PG8_LAS unsigned char* lds, int wid, int lane) const {
;     ...
;                     for (int i = 0; i < 4; ++i) { acc[ai][bj][m][0][i] = fsigmoid(acc[ai][bj][m][0][i]); acc[ai][bj][m][1][i] = fsigmoid(acc[ai][bj][m][1][i]); }
;             asm volatile("" : "+v"(acc[ai][0][0][0]), "+v"(acc[ai][0][0][1]), "+v"(acc[ai][1][0][0]), "+v"(acc[ai][1][0][1]), "+v"(acc[ai][0][1][0]), "+v"(acc[ai][0][1][1]), "+v"(acc[ai][1][1][0]), "+v"(acc[ai][1][1][1]),
;                              "+v"(acc[ai][0][2][0]), "+v"(acc[ai][0][2][1]), "+v"(acc[ai][1][2][0]), "+v"(acc[ai][1][2][1]), "+v"(acc[ai][0][3][0]), "+v"(acc[ai][0][3][1]), "+v"(acc[ai][1][3][0]), "+v"(acc[ai][1][3][1]));
; #pragma unroll
;             for (int m = 0; m < 4; ++m) {
; #pragma unroll
;                 for (int bj = 0; bj < 2; ++bj) { const u32x4 h4 = hv[m][bj], p4 = pl[m][bj];
;                     const f32x4 h0 = (f32x4){bf_lo(h4.x), bf_hi(h4.x), bf_lo(h4.y), bf_hi(h4.y)}, h1 = (f32x4){bf_lo(h4.z), bf_hi(h4.z), bf_lo(h4.w), bf_hi(h4.w)};
;                     const f32x4 p0 = (f32x4){bf_lo(p4.x), bf_hi(p4.x), bf_lo(p4.y), bf_hi(p4.y)}, p1 = (f32x4){bf_lo(p4.z), bf_hi(p4.z), bf_lo(p4.w), bf_hi(p4.w)};
; #pragma unroll
;                     for (int i = 0; i < 4; ++i) { acc[ai][bj][m][0][i] = h0[i] + p0[i] * acc[ai][bj][m][0][i]; acc[ai][bj][m][1][i] = h1[i] + p1[i] * acc[ai][bj][m][1][i]; } }
	v_rcp_f32_e32 v186, v64
	v_add_f32_e32 v64, 1.0, v65
	v_rcp_f32_e32 v207, v120
	v_add_f32_e32 v120, 1.0, v122
	v_rcp_f32_e32 v215, v104
	v_add_f32_e32 v104, 1.0, v106
	v_rcp_f32_e32 v183, v88
	v_add_f32_e32 v88, 1.0, v90
	v_rcp_f32_e32 v191, v64
	v_add_f32_e32 v64, 1.0, v66
	v_add_f32_e32 v44, 1.0, v44
	v_add_f32_e32 v16, 1.0, v16
	v_add_f32_e32 v8, 1.0, v8
	v_add_f32_e32 v0, 1.0, v0
	v_rcp_f32_e32 v199, v120
	v_rcp_f32_e32 v211, v104
	v_rcp_f32_e32 v179, v88
	v_rcp_f32_e32 v187, v64
	v_rcp_f32_e32 v64, v44
	v_add_f32_e32 v44, 1.0, v52
	v_rcp_f32_e32 v88, v16
	v_add_f32_e32 v16, 1.0, v20
	v_rcp_f32_e32 v104, v8
	v_add_f32_e32 v8, 1.0, v12
	v_rcp_f32_e32 v120, v0
	v_add_f32_e32 v0, 1.0, v4
	v_rcp_f32_e32 v69, v44
	v_add_f32_e32 v44, 1.0, v45
	v_mul_f32_e32 v45, 0xbfb8aa3b, v54
	v_rcp_f32_e32 v93, v16
	v_add_f32_e32 v16, 1.0, v17
	v_mul_f32_e32 v17, 0xbfb8aa3b, v22
	v_rcp_f32_e32 v109, v8
	v_add_f32_e32 v8, 1.0, v9
	v_mul_f32_e32 v9, 0xbfb8aa3b, v14
	v_rcp_f32_e32 v125, v0
	v_add_f32_e32 v0, 1.0, v1
	v_mul_f32_e32 v1, 0xbfb8aa3b, v6
	v_exp_f32_e32 v45, v45
	v_mul_f32_e32 v46, 0xbfb8aa3b, v46
	v_exp_f32_e32 v17, v17
	v_mul_f32_e32 v18, 0xbfb8aa3b, v18
	v_exp_f32_e32 v9, v9
	v_mul_f32_e32 v10, 0xbfb8aa3b, v10
	v_exp_f32_e32 v1, v1
	v_mul_f32_e32 v2, 0xbfb8aa3b, v2
	v_exp_f32_e32 v46, v46
	v_exp_f32_e32 v18, v18
	v_exp_f32_e32 v10, v10
	v_exp_f32_e32 v2, v2
	v_rcp_f32_e32 v65, v44
	v_add_f32_e32 v44, 1.0, v45
	v_mul_f32_e32 v45, 0xbfb8aa3b, v55
	v_rcp_f32_e32 v89, v16
	v_add_f32_e32 v16, 1.0, v17
	v_mul_f32_e32 v17, 0xbfb8aa3b, v23
	v_rcp_f32_e32 v105, v8
	v_add_f32_e32 v8, 1.0, v9
	v_mul_f32_e32 v9, 0xbfb8aa3b, v15
	v_rcp_f32_e32 v121, v0
	v_add_f32_e32 v0, 1.0, v1
	v_mul_f32_e32 v1, 0xbfb8aa3b, v7
	v_rcp_f32_e32 v70, v44
	v_add_f32_e32 v44, 1.0, v46
	v_exp_f32_e32 v45, v45
	v_mul_f32_e32 v46, 0xbfb8aa3b, v47
	v_rcp_f32_e32 v94, v16
	v_add_f32_e32 v16, 1.0, v18
	v_exp_f32_e32 v17, v17
	v_mul_f32_e32 v18, 0xbfb8aa3b, v19
	v_rcp_f32_e32 v110, v8
	v_add_f32_e32 v8, 1.0, v10
	v_exp_f32_e32 v9, v9
	v_mul_f32_e32 v10, 0xbfb8aa3b, v11
	v_rcp_f32_e32 v126, v0
	v_add_f32_e32 v0, 1.0, v2
	v_exp_f32_e32 v1, v1
	v_mul_f32_e32 v2, 0xbfb8aa3b, v3
	v_exp_f32_e32 v46, v46
	v_exp_f32_e32 v18, v18
	v_exp_f32_e32 v10, v10
	v_exp_f32_e32 v2, v2
	v_rcp_f32_e32 v66, v44
	v_add_f32_e32 v44, 1.0, v45
	v_rcp_f32_e32 v90, v16
	v_add_f32_e32 v16, 1.0, v17
	v_rcp_f32_e32 v106, v8
	v_add_f32_e32 v8, 1.0, v9
	v_rcp_f32_e32 v122, v0
	v_add_f32_e32 v0, 1.0, v1
	v_rcp_f32_e32 v71, v44
	v_add_f32_e32 v44, 1.0, v46
	v_rcp_f32_e32 v95, v16
	v_add_f32_e32 v16, 1.0, v18
	v_rcp_f32_e32 v111, v8
	v_add_f32_e32 v8, 1.0, v10
	v_rcp_f32_e32 v127, v0
	v_add_f32_e32 v0, 1.0, v2
	v_rcp_f32_e32 v67, v44
	v_rcp_f32_e32 v91, v16
	v_rcp_f32_e32 v107, v8
	v_rcp_f32_e32 v123, v0
	s_waitcnt vmcnt(15)
	v_lshlrev_b32_e32 v0, 16, v172
	v_and_b32_e32 v1, 0xffff0000, v172
	s_waitcnt vmcnt(13)
	v_lshlrev_b32_e32 v2, 16, v168
	v_and_b32_e32 v3, 0xffff0000, v168
	v_lshlrev_b32_e32 v6, 16, v169
	v_pk_fma_f32 v[4:5], v[204:205], v[2:3], v[0:1]
	v_lshlrev_b32_e32 v0, 16, v174
	v_and_b32_e32 v1, 0xffff0000, v174
	v_lshlrev_b32_e32 v2, 16, v170
	v_and_b32_e32 v3, 0xffff0000, v170
	v_pk_fma_f32 v[0:1], v[196:197], v[2:3], v[0:1]
	v_lshlrev_b32_e32 v2, 16, v173
	v_and_b32_e32 v3, 0xffff0000, v173
	v_and_b32_e32 v7, 0xffff0000, v169
	v_pk_fma_f32 v[6:7], v[206:207], v[6:7], v[2:3]
	v_lshlrev_b32_e32 v2, 16, v175
	v_and_b32_e32 v3, 0xffff0000, v175
	v_lshlrev_b32_e32 v8, 16, v171
	v_and_b32_e32 v9, 0xffff0000, v171
	v_pk_fma_f32 v[2:3], v[198:199], v[8:9], v[2:3]
	v_lshlrev_b32_e32 v8, 16, v164
	v_and_b32_e32 v9, 0xffff0000, v164
	s_waitcnt vmcnt(12)
	v_lshlrev_b32_e32 v10, 16, v160
	v_and_b32_e32 v11, 0xffff0000, v160
	v_pk_fma_f32 v[12:13], v[212:213], v[10:11], v[8:9]
	v_lshlrev_b32_e32 v8, 16, v166
	v_and_b32_e32 v9, 0xffff0000, v166
	v_lshlrev_b32_e32 v10, 16, v162
	v_and_b32_e32 v11, 0xffff0000, v162
	v_pk_fma_f32 v[8:9], v[208:209], v[10:11], v[8:9]
	v_lshlrev_b32_e32 v10, 16, v165
	v_and_b32_e32 v11, 0xffff0000, v165
	v_lshlrev_b32_e32 v14, 16, v161
	v_and_b32_e32 v15, 0xffff0000, v161
	v_pk_fma_f32 v[14:15], v[214:215], v[14:15], v[10:11]
	v_lshlrev_b32_e32 v10, 16, v167
	v_and_b32_e32 v11, 0xffff0000, v167
	v_lshlrev_b32_e32 v16, 16, v163
	v_and_b32_e32 v17, 0xffff0000, v163
	v_pk_fma_f32 v[10:11], v[210:211], v[16:17], v[10:11]
	s_waitcnt vmcnt(11)
	v_lshlrev_b32_e32 v16, 16, v156
	v_and_b32_e32 v17, 0xffff0000, v156
	s_waitcnt vmcnt(9)
	v_lshlrev_b32_e32 v18, 16, v152
	v_and_b32_e32 v19, 0xffff0000, v152
	v_pk_fma_f32 v[20:21], v[180:181], v[18:19], v[16:17]
	v_lshlrev_b32_e32 v16, 16, v158
	v_and_b32_e32 v17, 0xffff0000, v158
	v_lshlrev_b32_e32 v18, 16, v154
	v_and_b32_e32 v19, 0xffff0000, v154
	v_pk_fma_f32 v[16:17], v[176:177], v[18:19], v[16:17]
	v_lshlrev_b32_e32 v18, 16, v157
	v_and_b32_e32 v19, 0xffff0000, v157
	v_lshlrev_b32_e32 v22, 16, v153
	v_and_b32_e32 v23, 0xffff0000, v153
	v_pk_fma_f32 v[22:23], v[182:183], v[22:23], v[18:19]
	v_lshlrev_b32_e32 v18, 16, v159
	v_and_b32_e32 v19, 0xffff0000, v159
	v_lshlrev_b32_e32 v44, 16, v155
	v_and_b32_e32 v45, 0xffff0000, v155
	v_pk_fma_f32 v[18:19], v[178:179], v[44:45], v[18:19]
	v_lshlrev_b32_e32 v44, 16, v148
	v_and_b32_e32 v45, 0xffff0000, v148
	s_waitcnt vmcnt(8)
	v_lshlrev_b32_e32 v46, 16, v144
	v_and_b32_e32 v47, 0xffff0000, v144
	v_pk_fma_f32 v[52:53], v[188:189], v[46:47], v[44:45]
	v_lshlrev_b32_e32 v44, 16, v150
	v_and_b32_e32 v45, 0xffff0000, v150
	v_lshlrev_b32_e32 v46, 16, v146
	v_and_b32_e32 v47, 0xffff0000, v146
	v_pk_fma_f32 v[44:45], v[184:185], v[46:47], v[44:45]
	v_lshlrev_b32_e32 v46, 16, v149
	v_and_b32_e32 v47, 0xffff0000, v149
	v_lshlrev_b32_e32 v54, 16, v145
	v_and_b32_e32 v55, 0xffff0000, v145
	v_pk_fma_f32 v[54:55], v[190:191], v[54:55], v[46:47]
	v_lshlrev_b32_e32 v46, 16, v151
	v_and_b32_e32 v47, 0xffff0000, v151
	v_lshlrev_b32_e32 v144, 16, v147
	v_and_b32_e32 v145, 0xffff0000, v147
	v_pk_fma_f32 v[46:47], v[186:187], v[144:145], v[46:47]
	s_waitcnt vmcnt(7)
; #define PG8_STAMP(k) do { if ((k) == PROBE_T && (int)blockIdx.x == PROBE_BLOCK && wid == 0 && lane == 0) { const unsigned long long t_ = __builtin_amdgcn_s_memrealtime(); PG8_LAS unsigned* ms_ = (PG8_LAS unsigned*)(131072 + 320); ms_[14] = (unsigned)t_; ms_[15] = (unsigned)(t_ >> 32); } } while (0)
; #define PG8_STAMP(k) do { } while (0)
;     __device__ __forceinline__ bool run(const f32x4 (&v)[2][2][4][2], const Unit& u, int wr, int wc, int fr, int fq, PG8_LAS unsigned char* lds, int wid, int lane) const {
;     ...
;             for (int m = 0; m < 4; ++m) { float q = 0.f;
; #pragma unroll
;                 for (int bj = 0; bj < 2; ++bj)
; #pragma unroll
;                     for (int n = 0; n < 2; ++n) { const f32x4 x = v[ai][bj][m][n]; q += (x[0] * x[0] + x[1] * x[1]) + (x[2] * x[2] + x[3] * x[3]); }
;                 q += __shfl_xor(q, 16); q += __shfl_xor(q, 32);
;                 if (fq == 0) P[(ai * HALF + wr * 64 + m * 16 + fr) * 4 + wc] = q; }
;     __device__ __forceinline__ void fused(f32x4 (&acc)[2][2][4][2], const Unit& u, int wr, int wc, int fr, int fq, PG8_LAS unsigned char* lds, int wid, int lane) const {
;     ...
;                     for (int i = 0; i < 4; ++i) { acc[ai][bj][m][0][i] = h0[i] + p0[i] * acc[ai][bj][m][0][i]; acc[ai][bj][m][1][i] = h1[i] + p1[i] * acc[ai][bj][m][1][i]; } }
;                 asm volatile("" : "+v"(acc[ai][0][m][0]), "+v"(acc[ai][0][m][1]), "+v"(acc[ai][1][m][0]), "+v"(acc[ai][1][m][1]));
;             }
;         }
;         PG8_STAMP(31);
;         f32x4 gn[2][2];
; #pragma unroll
;         for (int bj = 0; bj < 2; ++bj) { gn[bj][0] = *(const f32x4*)(gain + col0 + bj * HALF); gn[bj][1] = *(const f32x4*)(gain + col0 + bj * HALF + 4); }
	v_lshlrev_b32_e32 v144, 16, v140
	v_and_b32_e32 v145, 0xffff0000, v140
	s_waitcnt vmcnt(5)
	v_lshlrev_b32_e32 v146, 16, v136
	v_and_b32_e32 v147, 0xffff0000, v136
	v_lshlrev_b32_e32 v140, 16, v141
	v_and_b32_e32 v141, 0xffff0000, v141
	v_lshlrev_b32_e32 v136, 16, v137
	v_and_b32_e32 v137, 0xffff0000, v137
	v_pk_fma_f32 v[68:69], v[68:69], v[146:147], v[144:145]
	v_lshlrev_b32_e32 v146, 16, v138
	v_and_b32_e32 v147, 0xffff0000, v138
	v_pk_fma_f32 v[70:71], v[70:71], v[136:137], v[140:141]
	v_lshlrev_b32_e32 v136, 16, v143
	v_and_b32_e32 v137, 0xffff0000, v143
	v_lshlrev_b32_e32 v138, 16, v139
	v_and_b32_e32 v139, 0xffff0000, v139
	v_pk_fma_f32 v[66:67], v[66:67], v[138:139], v[136:137]
	v_lshlrev_b32_e32 v136, 16, v132
	v_and_b32_e32 v137, 0xffff0000, v132
	s_waitcnt vmcnt(4)
	v_lshlrev_b32_e32 v138, 16, v128
	v_and_b32_e32 v139, 0xffff0000, v128
	v_lshlrev_b32_e32 v132, 16, v133
	v_and_b32_e32 v133, 0xffff0000, v133
	v_lshlrev_b32_e32 v128, 16, v129
	v_and_b32_e32 v129, 0xffff0000, v129
	v_pk_fma_f32 v[92:93], v[92:93], v[138:139], v[136:137]
	v_lshlrev_b32_e32 v138, 16, v130
	v_and_b32_e32 v139, 0xffff0000, v130
	v_pk_fma_f32 v[94:95], v[94:95], v[128:129], v[132:133]
	v_lshlrev_b32_e32 v128, 16, v135
	v_and_b32_e32 v129, 0xffff0000, v135
	v_lshlrev_b32_e32 v130, 16, v131
	v_and_b32_e32 v131, 0xffff0000, v131
	v_pk_fma_f32 v[90:91], v[90:91], v[130:131], v[128:129]
	s_waitcnt vmcnt(3)
	v_lshlrev_b32_e32 v128, 16, v220
	v_and_b32_e32 v129, 0xffff0000, v220
	s_waitcnt vmcnt(1)
	v_lshlrev_b32_e32 v130, 16, v216
	v_and_b32_e32 v131, 0xffff0000, v216
	v_pk_fma_f32 v[108:109], v[108:109], v[130:131], v[128:129]
	v_lshlrev_b32_e32 v128, 16, v222
	v_and_b32_e32 v129, 0xffff0000, v222
	v_lshlrev_b32_e32 v130, 16, v218
	v_and_b32_e32 v131, 0xffff0000, v218
	v_pk_fma_f32 v[104:105], v[104:105], v[130:131], v[128:129]
	v_lshlrev_b32_e32 v128, 16, v221
	v_and_b32_e32 v129, 0xffff0000, v221
	v_lshlrev_b32_e32 v130, 16, v217
	v_and_b32_e32 v131, 0xffff0000, v217
	v_pk_fma_f32 v[110:111], v[110:111], v[130:131], v[128:129]
	v_lshlrev_b32_e32 v128, 16, v223
	v_and_b32_e32 v129, 0xffff0000, v223
	v_lshlrev_b32_e32 v130, 16, v219
	v_and_b32_e32 v131, 0xffff0000, v219
	v_pk_fma_f32 v[106:107], v[106:107], v[130:131], v[128:129]
	v_lshlrev_b32_e32 v128, 16, v200
	v_and_b32_e32 v129, 0xffff0000, v200
	s_waitcnt vmcnt(0)
	v_lshlrev_b32_e32 v130, 16, v192
	v_and_b32_e32 v131, 0xffff0000, v192
	v_pk_fma_f32 v[124:125], v[124:125], v[130:131], v[128:129]
	v_lshlrev_b32_e32 v128, 16, v202
	v_and_b32_e32 v129, 0xffff0000, v202
	v_lshlrev_b32_e32 v130, 16, v194
	v_and_b32_e32 v131, 0xffff0000, v194
	v_pk_fma_f32 v[120:121], v[120:121], v[130:131], v[128:129]
	v_lshlrev_b32_e32 v128, 16, v201
	v_and_b32_e32 v129, 0xffff0000, v201
	v_lshlrev_b32_e32 v130, 16, v193
	v_and_b32_e32 v131, 0xffff0000, v193
	v_lshlrev_b32_e32 v144, 16, v142
	v_and_b32_e32 v145, 0xffff0000, v142
	v_lshlrev_b32_e32 v136, 16, v134
	v_and_b32_e32 v137, 0xffff0000, v134
	v_pk_fma_f32 v[126:127], v[126:127], v[130:131], v[128:129]
	v_lshlrev_b32_e32 v128, 16, v203
	v_and_b32_e32 v129, 0xffff0000, v203
	v_lshlrev_b32_e32 v130, 16, v195
	v_and_b32_e32 v131, 0xffff0000, v195
	v_pk_fma_f32 v[64:65], v[64:65], v[146:147], v[144:145]
	v_pk_fma_f32 v[88:89], v[88:89], v[138:139], v[136:137]
	v_pk_fma_f32 v[122:123], v[122:123], v[130:131], v[128:129]
	v_lshlrev_b32_e32 v132, 2, v224
	global_load_dwordx4 v[136:139], v132, s[28:29] offset:16
	global_load_dwordx4 v[140:143], v132, s[28:29]
	global_load_dwordx4 v[128:131], v132, s[28:29] offset:528
	s_nop 0
	global_load_dwordx4 v[132:135], v132, s[28:29] offset:512
	v_mul_f32_e32 v146, v29, v29
	v_mul_f32_e32 v147, v31, v31
	v_fmac_f32_e32 v146, v28, v28
	v_fmac_f32_e32 v147, v30, v30
	v_add_f32_e32 v146, v146, v147
	v_mul_f32_e32 v147, v25, v25
	v_mul_f32_e32 v148, v27, v27
	v_fmac_f32_e32 v147, v24, v24
	v_fmac_f32_e32 v148, v26, v26
	v_add_f32_e32 v147, v147, v148
	v_add_f32_e32 v146, v146, v147
	v_mul_f32_e32 v147, v37, v37
	v_mul_f32_e32 v148, v39, v39
	v_fmac_f32_e32 v147, v36, v36
	v_fmac_f32_e32 v148, v38, v38
	v_and_b32_e32 v145, 64, v244
	v_add_f32_e32 v147, v147, v148
	v_xor_b32_e32 v144, 16, v244
	v_add_u32_e32 v145, 64, v145
	v_add_f32_e32 v146, v147, v146
	v_mul_f32_e32 v147, v33, v33
	v_mul_f32_e32 v148, v35, v35
	v_cmp_lt_i32_e32 vcc, v144, v145
	v_fmac_f32_e32 v147, v32, v32
	v_fmac_f32_e32 v148, v34, v34
	v_cndmask_b32_e32 v144, v244, v144, vcc
	v_add_f32_e32 v147, v147, v148
	v_lshlrev_b32_e32 v144, 2, v144
	v_add_f32_e32 v146, v147, v146
	v_xor_b32_e32 v147, 32, v244
	v_cmp_lt_i32_e32 vcc, v147, v145
	s_waitcnt lgkmcnt(0)
	v_cndmask_b32_e32 v145, v244, v147, vcc
	v_lshlrev_b32_e32 v147, 2, v145
	v_mov_b32_e32 v148, v146
	v_mov_b32_e32 v149, v146
	s_nop 1
	v_permlane16_swap_b32_e32 v148, v149
	v_add_f32_e32 v148, v148, v149
	v_mov_b32_e32 v149, v148
	s_nop 1
	v_permlane32_swap_b32_e32 v148, v149
	v_add_f32_e32 v148, v148, v149
	v_and_b32_e32 v146, 63, v249
	v_cmp_gt_u32_e32 vcc, 16, v146
	v_lshl_add_u32 v145, v248, 4, s52
	s_and_saveexec_b64 s[0:1], vcc
	s_cbranch_execz .LBB0_586
	s_waitcnt lgkmcnt(0)
	ds_write_b32 v145, v148
;     __device__ __forceinline__ bool run(const f32x4 (&v)[2][2][4][2], const Unit& u, int wr, int wc, int fr, int fq, PG8_LAS unsigned char* lds, int wid, int lane) const {
;     ...
;             for (int m = 0; m < 4; ++m) { float q = 0.f;
; #pragma unroll
;                 for (int bj = 0; bj < 2; ++bj)
; #pragma unroll
;                     for (int n = 0; n < 2; ++n) { const f32x4 x = v[ai][bj][m][n]; q += (x[0] * x[0] + x[1] * x[1]) + (x[2] * x[2] + x[3] * x[3]); }
;                 q += __shfl_xor(q, 16); q += __shfl_xor(q, 32);
;                 if (fq == 0) P[(ai * HALF + wr * 64 + m * 16 + fr) * 4 + wc] = q; }
.LBB0_586:
	s_or_b64 exec, exec, s[0:1]
	v_mul_f32_e32 v148, v49, v49
	s_waitcnt lgkmcnt(0)
	v_mul_f32_e32 v149, v51, v51
	v_fmac_f32_e32 v148, v48, v48
	v_fmac_f32_e32 v149, v50, v50
	v_add_f32_e32 v148, v148, v149
	v_mul_f32_e32 v149, v41, v41
	v_mul_f32_e32 v150, v43, v43
	v_fmac_f32_e32 v149, v40, v40
	v_fmac_f32_e32 v150, v42, v42
	v_add_f32_e32 v149, v149, v150
	v_add_f32_e32 v148, v148, v149
	v_mul_f32_e32 v149, v61, v61
	v_mul_f32_e32 v150, v63, v63
	v_fmac_f32_e32 v149, v60, v60
	v_fmac_f32_e32 v150, v62, v62
	v_add_f32_e32 v149, v149, v150
	v_add_f32_e32 v148, v149, v148
	v_mul_f32_e32 v149, v57, v57
	v_mul_f32_e32 v150, v59, v59
	v_fmac_f32_e32 v149, v56, v56
	v_fmac_f32_e32 v150, v58, v58
	v_add_f32_e32 v149, v149, v150
	v_add_f32_e32 v148, v149, v148
	s_waitcnt lgkmcnt(0)
	v_mov_b32_e32 v149, v148
	s_nop 1
	v_permlane16_swap_b32_e32 v148, v149
	v_add_f32_e32 v148, v148, v149
	v_mov_b32_e32 v149, v148
	s_nop 1
	v_permlane32_swap_b32_e32 v148, v149
	v_add_f32_e32 v148, v148, v149
	s_and_saveexec_b64 s[0:1], vcc
	s_cbranch_execz .LBB0_588
	s_waitcnt lgkmcnt(0)
	ds_write_b32 v145, v148 offset:256
.LBB0_588:
	s_or_b64 exec, exec, s[0:1]
	v_mul_f32_e32 v148, v77, v77
	s_waitcnt lgkmcnt(0)
	v_mul_f32_e32 v149, v79, v79
	v_fmac_f32_e32 v148, v76, v76
	v_fmac_f32_e32 v149, v78, v78
	v_add_f32_e32 v148, v148, v149
	v_mul_f32_e32 v149, v73, v73
	v_mul_f32_e32 v150, v75, v75
	v_fmac_f32_e32 v149, v72, v72
	v_fmac_f32_e32 v150, v74, v74
	v_add_f32_e32 v149, v149, v150
	v_add_f32_e32 v148, v148, v149
	v_mul_f32_e32 v149, v85, v85
	v_mul_f32_e32 v150, v87, v87
	v_fmac_f32_e32 v149, v84, v84
	v_fmac_f32_e32 v150, v86, v86
	v_add_f32_e32 v149, v149, v150
	v_add_f32_e32 v148, v149, v148
	v_mul_f32_e32 v149, v81, v81
	v_mul_f32_e32 v150, v83, v83
	v_fmac_f32_e32 v149, v80, v80
	v_fmac_f32_e32 v150, v82, v82
	v_add_f32_e32 v149, v149, v150
	v_add_f32_e32 v148, v149, v148
	s_waitcnt lgkmcnt(0)
	v_mov_b32_e32 v149, v148
	s_nop 1
	v_permlane16_swap_b32_e32 v148, v149
	v_add_f32_e32 v148, v148, v149
	v_mov_b32_e32 v149, v148
	s_nop 1
	v_permlane32_swap_b32_e32 v148, v149
	v_add_f32_e32 v148, v148, v149
	s_and_saveexec_b64 s[0:1], vcc
	s_cbranch_execz .LBB0_590
	s_waitcnt lgkmcnt(0)
	ds_write_b32 v145, v148 offset:512
.LBB0_590:
	s_or_b64 exec, exec, s[0:1]
	v_mul_f32_e32 v148, v101, v101
	s_waitcnt lgkmcnt(0)
	v_mul_f32_e32 v149, v103, v103
	v_fmac_f32_e32 v148, v100, v100
	v_fmac_f32_e32 v149, v102, v102
	v_add_f32_e32 v148, v148, v149
	v_mul_f32_e32 v149, v97, v97
	v_mul_f32_e32 v150, v99, v99
	v_fmac_f32_e32 v149, v96, v96
	v_fmac_f32_e32 v150, v98, v98
	v_add_f32_e32 v149, v149, v150
	v_add_f32_e32 v148, v148, v149
	v_mul_f32_e32 v149, v117, v117
	v_mul_f32_e32 v150, v119, v119
	v_fmac_f32_e32 v149, v116, v116
	v_fmac_f32_e32 v150, v118, v118
	v_add_f32_e32 v149, v149, v150
	v_add_f32_e32 v148, v149, v148
	v_mul_f32_e32 v149, v113, v113
	v_mul_f32_e32 v150, v115, v115
	v_fmac_f32_e32 v149, v112, v112
	v_fmac_f32_e32 v150, v114, v114
	v_add_f32_e32 v149, v149, v150
	v_add_f32_e32 v148, v149, v148
	s_waitcnt lgkmcnt(0)
	v_mov_b32_e32 v149, v148
	s_nop 1
	v_permlane16_swap_b32_e32 v148, v149
	v_add_f32_e32 v148, v148, v149
	v_mov_b32_e32 v149, v148
	s_nop 1
	v_permlane32_swap_b32_e32 v148, v149
	v_add_f32_e32 v148, v148, v149
	s_and_saveexec_b64 s[0:1], vcc
	s_cbranch_execz .LBB0_592
	s_waitcnt lgkmcnt(0)
	ds_write_b32 v145, v148 offset:768
.LBB0_592:
	s_or_b64 exec, exec, s[0:1]
	v_mul_f32_e32 v148, v5, v5
	s_waitcnt lgkmcnt(0)
	v_mul_f32_e32 v149, v7, v7
	v_fmac_f32_e32 v148, v4, v4
	v_fmac_f32_e32 v149, v6, v6
	v_add_f32_e32 v148, v148, v149
	v_mul_f32_e32 v149, v1, v1
	v_mul_f32_e32 v150, v3, v3
	v_fmac_f32_e32 v149, v0, v0
	v_fmac_f32_e32 v150, v2, v2
	v_add_f32_e32 v149, v149, v150
	v_add_f32_e32 v148, v148, v149
	v_mul_f32_e32 v149, v13, v13
	v_mul_f32_e32 v150, v15, v15
	v_fmac_f32_e32 v149, v12, v12
	v_fmac_f32_e32 v150, v14, v14
	v_add_f32_e32 v149, v149, v150
	v_add_f32_e32 v148, v149, v148
	v_mul_f32_e32 v149, v9, v9
	v_mul_f32_e32 v150, v11, v11
	v_fmac_f32_e32 v149, v8, v8
	v_fmac_f32_e32 v150, v10, v10
	v_add_f32_e32 v149, v149, v150
	v_add_f32_e32 v148, v149, v148
	s_waitcnt lgkmcnt(0)
	v_mov_b32_e32 v149, v148
	s_nop 1
	v_permlane16_swap_b32_e32 v148, v149
	v_add_f32_e32 v148, v148, v149
	v_mov_b32_e32 v149, v148
	s_nop 1
	v_permlane32_swap_b32_e32 v148, v149
	v_add_f32_e32 v148, v148, v149
	s_and_saveexec_b64 s[0:1], vcc
	s_cbranch_execz .LBB0_594
	s_waitcnt lgkmcnt(0)
	ds_write_b32 v145, v148 offset:2048
;     __device__ __forceinline__ bool run(const f32x4 (&v)[2][2][4][2], const Unit& u, int wr, int wc, int fr, int fq, PG8_LAS unsigned char* lds, int wid, int lane) const {
;     ...
;             for (int m = 0; m < 4; ++m) { float q = 0.f;
; #pragma unroll
;                 for (int bj = 0; bj < 2; ++bj)
; #pragma unroll
;                     for (int n = 0; n < 2; ++n) { const f32x4 x = v[ai][bj][m][n]; q += (x[0] * x[0] + x[1] * x[1]) + (x[2] * x[2] + x[3] * x[3]); }
;                 q += __shfl_xor(q, 16); q += __shfl_xor(q, 32);
;                 if (fq == 0) P[(ai * HALF + wr * 64 + m * 16 + fr) * 4 + wc] = q; }
.LBB0_594:
	s_or_b64 exec, exec, s[0:1]
	v_mul_f32_e32 v148, v21, v21
	s_waitcnt lgkmcnt(0)
	v_mul_f32_e32 v149, v23, v23
	v_fmac_f32_e32 v148, v20, v20
	v_fmac_f32_e32 v149, v22, v22
	v_add_f32_e32 v148, v148, v149
	v_mul_f32_e32 v149, v17, v17
	v_mul_f32_e32 v150, v19, v19
	v_fmac_f32_e32 v149, v16, v16
	v_fmac_f32_e32 v150, v18, v18
	v_add_f32_e32 v149, v149, v150
	v_add_f32_e32 v148, v148, v149
	v_mul_f32_e32 v149, v53, v53
	v_mul_f32_e32 v150, v55, v55
	v_fmac_f32_e32 v149, v52, v52
	v_fmac_f32_e32 v150, v54, v54
	v_add_f32_e32 v149, v149, v150
	v_add_f32_e32 v148, v149, v148
	v_mul_f32_e32 v149, v45, v45
	v_mul_f32_e32 v150, v47, v47
	v_fmac_f32_e32 v149, v44, v44
	v_fmac_f32_e32 v150, v46, v46
	v_add_f32_e32 v149, v149, v150
	v_add_f32_e32 v148, v149, v148
	s_waitcnt lgkmcnt(0)
	v_mov_b32_e32 v149, v148
	s_nop 1
	v_permlane16_swap_b32_e32 v148, v149
	v_add_f32_e32 v148, v148, v149
	v_mov_b32_e32 v149, v148
	s_nop 1
	v_permlane32_swap_b32_e32 v148, v149
	v_add_f32_e32 v148, v148, v149
	s_and_saveexec_b64 s[0:1], vcc
	s_cbranch_execz .LBB0_596
	s_waitcnt lgkmcnt(0)
	ds_write_b32 v145, v148 offset:2304
.LBB0_596:
	s_or_b64 exec, exec, s[0:1]
	v_mul_f32_e32 v148, v69, v69
	s_waitcnt lgkmcnt(0)
	v_mul_f32_e32 v149, v71, v71
	v_fmac_f32_e32 v148, v68, v68
	v_fmac_f32_e32 v149, v70, v70
	v_add_f32_e32 v148, v148, v149
	v_mul_f32_e32 v149, v65, v65
	v_mul_f32_e32 v150, v67, v67
	v_fmac_f32_e32 v149, v64, v64
	v_fmac_f32_e32 v150, v66, v66
	v_add_f32_e32 v149, v149, v150
	v_add_f32_e32 v148, v148, v149
	v_mul_f32_e32 v149, v93, v93
	v_mul_f32_e32 v150, v95, v95
	v_fmac_f32_e32 v149, v92, v92
	v_fmac_f32_e32 v150, v94, v94
	v_add_f32_e32 v149, v149, v150
	v_add_f32_e32 v148, v149, v148
	v_mul_f32_e32 v149, v89, v89
	v_mul_f32_e32 v150, v91, v91
	v_fmac_f32_e32 v149, v88, v88
	v_fmac_f32_e32 v150, v90, v90
	v_add_f32_e32 v149, v149, v150
	v_add_f32_e32 v148, v149, v148
	s_waitcnt lgkmcnt(0)
	v_mov_b32_e32 v149, v148
	s_nop 1
	v_permlane16_swap_b32_e32 v148, v149
	v_add_f32_e32 v148, v148, v149
	v_mov_b32_e32 v149, v148
	s_nop 1
	v_permlane32_swap_b32_e32 v148, v149
	v_add_f32_e32 v148, v148, v149
	s_and_saveexec_b64 s[0:1], vcc
	s_cbranch_execz .LBB0_598
	s_waitcnt lgkmcnt(0)
	ds_write_b32 v145, v148 offset:2560
.LBB0_598:
	s_or_b64 exec, exec, s[0:1]
	v_mul_f32_e32 v148, v109, v109
	s_waitcnt lgkmcnt(0)
	v_mul_f32_e32 v149, v111, v111
	v_fmac_f32_e32 v148, v108, v108
	v_fmac_f32_e32 v149, v110, v110
	v_add_f32_e32 v148, v148, v149
	v_mul_f32_e32 v149, v105, v105
	v_mul_f32_e32 v150, v107, v107
	v_fmac_f32_e32 v149, v104, v104
	v_fmac_f32_e32 v150, v106, v106
	v_add_f32_e32 v149, v149, v150
	v_add_f32_e32 v148, v148, v149
	v_mul_f32_e32 v149, v125, v125
	v_mul_f32_e32 v150, v127, v127
	v_fmac_f32_e32 v149, v124, v124
	v_fmac_f32_e32 v150, v126, v126
	v_add_f32_e32 v149, v149, v150
	v_add_f32_e32 v148, v149, v148
	v_mul_f32_e32 v149, v121, v121
	v_mul_f32_e32 v150, v123, v123
	v_fmac_f32_e32 v149, v120, v120
	v_fmac_f32_e32 v150, v122, v122
	v_add_f32_e32 v149, v149, v150
	v_add_f32_e32 v148, v149, v148
	s_waitcnt lgkmcnt(0)
	v_mov_b32_e32 v144, v148
	v_mov_b32_e32 v147, v148
	s_nop 1
	v_permlane16_swap_b32_e32 v144, v147
	v_add_f32_e32 v144, v144, v147
	v_mov_b32_e32 v147, v144
	s_nop 1
	v_permlane32_swap_b32_e32 v144, v147
	v_add_f32_e32 v144, v144, v147
	s_and_saveexec_b64 s[0:1], vcc
	s_cbranch_execz .LBB0_600
	s_waitcnt lgkmcnt(0)
	ds_write_b32 v145, v144 offset:2816
